# E20: down-phase skinny unit split over 4 CUs by K-chunk (128 CUs busy), f32 partial combine via ws window + per-unit counter (both layers); on E10 final
# speedup vs baseline: 1.0120x; 1.0089x over previous
.LBB0_881:
	v_readlane_b32 s4, v244, 3
	s_cmp_lt_i32 s4, 6
	s_cselect_b64 s[8:9], -1, 0
	s_and_b64 s[0:1], s[8:9], s[0:1]
	s_andn2_b64 vcc, exec, s[0:1]
	v_readlane_b32 s5, v244, 4
	s_cbranch_vccnz .LBB0_987
	s_add_u32 s10, s82, 0x1e00000
	s_addc_u32 s11, s83, 0
	s_cmpk_lt_i32 s2, 0x80
	s_cbranch_scc1 .LBB0_884
	v_lshrrev_b32_e32 v3, 1, v217
	s_cbranch_execz .LBB0_885
	s_branch .LBB0_915
.LBB0_884:
.LBB0_885:
	s_waitcnt lgkmcnt(0)
	v_lshrrev_b32_e32 v4, 3, v217
	s_add_u32 s16, s80, 0x4000000
	v_and_b32_e32 v168, 4, v4
	v_add_u32_e32 v4, 64, v224
	s_addc_u32 s17, s81, 0
	v_cmp_lt_i32_e32 vcc, v223, v4
	s_add_u32 s18, s82, 0x184000
	s_addc_u32 s19, s83, 0
	v_cndmask_b32_e32 v4, v217, v223, vcc
	v_lshlrev_b32_e32 v169, 2, v4
	v_and_b32_e32 v4, 32, v217
	v_mov_b32_e32 v133, 0
	v_lshlrev_b32_e32 v132, 1, v168
	s_mov_b64 s[12:13], src_shared_base
	s_movk_i32 s3, 0x810
	v_lshrrev_b32_e32 v3, 1, v217
	s_add_u32 s20, s82, 0xa000
	v_cmp_eq_u32_e64 s[0:1], 0, v4
	v_lshl_add_u64 v[4:5], s[82:83], 0, v[132:133]
	s_mov_b64 s[6:7], 0x6100000
	v_mad_u32_u24 v137, v212, s3, 0
	v_and_b32_e32 v166, 16, v3
	v_lshl_add_u32 v167, v213, 2, 0
	s_addc_u32 s21, s83, 0
	v_cmp_eq_u32_e64 s[4:5], 0, v213
	v_lshl_add_u64 v[134:135], v[4:5], 0, s[6:7]
	s_lshr_b32 s98, s2, 5
	s_and_b32 s99, s2, 31
	s_lshl_b32 s12, s99, 5
	s_lshl_b32 s33, s88, 5
	v_lshlrev_b32_e32 v136, 4, v213
	v_mov_b32_e32 v139, s13
	s_mov_b64 s[22:23], 0x1e00800
	s_mov_b64 s[24:25], 0x400
	s_mov_b32 s38, 0xe400000
	s_mov_b32 s39, 0xe401000
	s_mov_b32 s40, 0xe402000
	s_mov_b32 s41, 0xe403000
	s_mov_b64 s[26:27], 0x800
	s_mov_b64 s[28:29], 0x10000
	s_movk_i32 s42, 0x80
	s_movk_i32 s43, 0xffe0
	v_mov_b32_e32 v170, 0x358637bd
	s_mov_b32 s44, 0xf800000
	v_mov_b32_e32 v171, 0x260
	s_and_b32 s30, s2, 31
	s_branch .LBB0_887

.LBB0_887:
	s_lshl_b32 s100, s98, 11
	s_add_u32 s100, s10, s100
	s_addc_u32 s101, s11, 0
	s_getreg_b32 s6, hwreg(HW_REG_HW_ID, 0, 6)
	s_and_b32 s6, s6, 63
	s_lshl_b32 s6, s6, 2
	s_add_i32 s6, s6, 0
	s_add_i32 s6, s6, 0x23e00
	v_mov_b32_e32 v138, s6
	flat_load_dword v4, v[138:139] sc0 sc1
	s_waitcnt vmcnt(0)
	s_movk_i32 s6, 0x1000
	s_lshl_b32 s45, s30, 5
	s_mov_b32 s31, 1
	v_mov_b32_e32 v35, 0
	v_mov_b32_e32 v34, 0
	v_mov_b32_e32 v33, 0
	v_mov_b32_e32 v32, 0
	v_mov_b32_e32 v31, 0
	v_mov_b32_e32 v30, 0
	v_mov_b32_e32 v29, 0
	v_mov_b32_e32 v28, 0
	v_mov_b32_e32 v27, 0
	v_mov_b32_e32 v26, 0
	v_mov_b32_e32 v25, 0
	v_mov_b32_e32 v24, 0
	v_mov_b32_e32 v23, 0
	v_mov_b32_e32 v22, 0
	v_mov_b32_e32 v21, 0
	v_mov_b32_e32 v20, 0
	v_mov_b32_e32 v19, 0
	v_mov_b32_e32 v18, 0
	v_mov_b32_e32 v17, 0
	v_mov_b32_e32 v16, 0
	v_mov_b32_e32 v15, 0
	v_mov_b32_e32 v14, 0
	v_mov_b32_e32 v13, 0
	v_mov_b32_e32 v12, 0
	v_mov_b32_e32 v11, 0
	v_mov_b32_e32 v10, 0
	v_mov_b32_e32 v9, 0
	v_mov_b32_e32 v8, 0
	v_mov_b32_e32 v7, 0
	v_mov_b32_e32 v6, 0
	v_mov_b32_e32 v5, 0
	s_cmp_lt_i32 s31, 1
	s_waitcnt lgkmcnt(0)
	v_readfirstlane_b32 s7, v4
	s_nop 1
	v_lshl_add_u32 v138, s7, 6, v217
	v_ashrrev_i32_e32 v68, 7, v138
	v_ashrrev_i32_e32 v172, 6, v138
	v_and_b32_e32 v140, -2, v68
	v_and_b32_e32 v173, 3, v172
	v_ashrrev_i32_e32 v141, 31, v140
	v_mov_b32_e32 v4, 0
	s_cbranch_scc1 .LBB0_892
	v_add_u32_e32 v8, 0x200, v138
	v_add_u32_e32 v12, 0x600, v138
	v_add_u32_e32 v16, 0xa00, v138
	v_add_u32_e32 v20, 0xe00, v138
	v_lshlrev_b32_e32 v4, 4, v138
	v_ashrrev_i32_e32 v22, 7, v8
	v_add_u32_e32 v10, 0x400, v138
	v_ashrrev_i32_e32 v24, 7, v12
	v_add_u32_e32 v14, 0x800, v138
	v_ashrrev_i32_e32 v26, 7, v16
	v_add_u32_e32 v18, 0xc00, v138
	v_ashrrev_i32_e32 v28, 7, v20
	v_and_b32_e32 v132, 0x7f0, v4
	v_add_u32_e32 v8, s45, v22
	v_ashrrev_i32_e32 v23, 7, v10
	v_add_u32_e32 v12, s45, v24
	v_ashrrev_i32_e32 v25, 7, v14
	v_add_u32_e32 v16, s45, v26
	v_ashrrev_i32_e32 v27, 7, v18
	v_add_u32_e32 v20, s45, v28
	v_lshl_add_u64 v[4:5], s[100:101], 0, v[132:133]
	v_add_u32_e32 v6, s45, v68
	v_mad_i64_i32 v[8:9], s[34:35], v8, s6, 0
	v_add_u32_e32 v10, s45, v23
	v_mad_i64_i32 v[12:13], s[34:35], v12, s6, 0
	v_add_u32_e32 v14, s45, v25
	v_mad_i64_i32 v[16:17], s[34:35], v16, s6, 0
	v_add_u32_e32 v18, s45, v27
	v_mad_i64_i32 v[20:21], s[34:35], v20, s6, 0
	v_mad_i64_i32 v[6:7], s[34:35], v6, s6, 0
	v_mad_i64_i32 v[10:11], s[34:35], v10, s6, 0
	v_mad_i64_i32 v[14:15], s[34:35], v14, s6, 0
	v_mad_i64_i32 v[18:19], s[34:35], v18, s6, 0
	v_lshl_add_u64 v[20:21], v[20:21], 1, v[4:5]
	v_lshl_add_u64 v[16:17], v[16:17], 1, v[4:5]
	v_lshl_add_u64 v[12:13], v[12:13], 1, v[4:5]
	v_lshl_add_u64 v[8:9], v[8:9], 1, v[4:5]
	v_lshl_add_u64 v[18:19], v[18:19], 1, v[4:5]
	global_load_dwordx4 v[64:67], v[20:21], off
	global_load_dwordx4 v[60:63], v[18:19], off
	v_lshl_add_u64 v[14:15], v[14:15], 1, v[4:5]
	global_load_dwordx4 v[56:59], v[16:17], off
	global_load_dwordx4 v[52:55], v[14:15], off
	v_lshl_add_u64 v[10:11], v[10:11], 1, v[4:5]
	global_load_dwordx4 v[48:51], v[12:13], off
	global_load_dwordx4 v[44:47], v[10:11], off
	v_lshl_add_u64 v[4:5], v[6:7], 1, v[4:5]
	global_load_dwordx4 v[40:43], v[8:9], off
	global_load_dwordx4 v[36:39], v[4:5], off
	s_ashr_i32 s7, s6, 31
	v_add_u32_e32 v16, s12, v68
	v_and_b32_e32 v4, 0x7f, v138
	s_ashr_i32 s36, s6, 4
	v_add_u32_e32 v6, 0, v132
	s_lshl_b32 s46, s6, 1
	v_ashrrev_i32_e32 v17, 31, v16
	v_lshlrev_b32_e32 v132, 4, v4
	s_lshr_b64 s[6:7], s[6:7], 31
	v_mad_u64_u32 v[4:5], s[34:35], s46, v16, v[132:133]
	v_mul_lo_u32 v17, s46, v17
	v_mul_lo_u32 v16, s6, v16
	v_add3_u32 v5, v16, v5, v17
	v_add_u32_e32 v16, s12, v22
	v_ashrrev_i32_e32 v17, 31, v16
	v_lshl_add_u64 v[142:143], v[4:5], 0, s[22:23]
	v_mad_u64_u32 v[4:5], s[34:35], s46, v16, v[132:133]
	v_mul_lo_u32 v16, s6, v16
	v_mul_lo_u32 v17, s46, v17
	v_add3_u32 v5, v16, v5, v17
	v_add_u32_e32 v16, s12, v23
	v_ashrrev_i32_e32 v17, 31, v16
	v_lshl_add_u64 v[144:145], v[4:5], 0, s[22:23]
	v_mad_u64_u32 v[4:5], s[34:35], s46, v16, v[132:133]
	v_mul_lo_u32 v16, s6, v16
	v_mul_lo_u32 v17, s46, v17
	v_add3_u32 v5, v16, v5, v17
	v_add_u32_e32 v16, s12, v24
	v_ashrrev_i32_e32 v17, 31, v16
	v_lshl_add_u64 v[146:147], v[4:5], 0, s[22:23]
	v_mad_u64_u32 v[4:5], s[34:35], s46, v16, v[132:133]
	v_mul_lo_u32 v16, s6, v16
	v_mul_lo_u32 v17, s46, v17
	v_add3_u32 v5, v16, v5, v17
	v_add_u32_e32 v16, s12, v25
	v_ashrrev_i32_e32 v17, 31, v16
	v_lshl_add_u64 v[148:149], v[4:5], 0, s[22:23]
	v_mad_u64_u32 v[4:5], s[34:35], s46, v16, v[132:133]
	v_mul_lo_u32 v16, s6, v16
	v_mul_lo_u32 v17, s46, v17
	v_add3_u32 v5, v16, v5, v17
	v_add_u32_e32 v16, s12, v26
	v_ashrrev_i32_e32 v17, 31, v16
	v_lshl_add_u64 v[150:151], v[4:5], 0, s[22:23]
	v_mad_u64_u32 v[4:5], s[34:35], s46, v16, v[132:133]
	v_mul_lo_u32 v16, s6, v16
	v_mul_lo_u32 v17, s46, v17
	v_add3_u32 v5, v16, v5, v17
	v_add_u32_e32 v16, s12, v27
	v_ashrrev_i32_e32 v17, 31, v16
	v_lshl_add_u64 v[152:153], v[4:5], 0, s[22:23]
	v_mad_u64_u32 v[4:5], s[34:35], s46, v16, v[132:133]
	v_mul_lo_u32 v16, s6, v16
	v_mul_lo_u32 v17, s46, v17
	v_add3_u32 v5, v16, v5, v17
	v_add_u32_e32 v16, s12, v28
	v_ashrrev_i32_e32 v17, 31, v16
	v_lshl_add_u64 v[154:155], v[4:5], 0, s[22:23]
	v_mad_u64_u32 v[4:5], s[34:35], s46, v16, v[132:133]
	v_mul_lo_u32 v16, s6, v16
	v_mul_lo_u32 v17, s46, v17
	v_add3_u32 v5, v16, v5, v17
	v_lshl_add_u64 v[156:157], v[4:5], 0, s[22:23]
	v_mad_i64_i32 v[4:5], s[6:7], s36, v140, 0
	v_lshlrev_b64 v[4:5], 10, v[4:5]
	v_lshlrev_b32_e32 v16, 8, v138
	v_or_b32_e32 v4, v136, v4
	v_and_b32_e32 v132, 0xc000, v16
	v_lshl_add_u64 v[158:159], v[4:5], 0, v[132:133]
	v_lshl_add_u32 v158, s98, 16, v158
	v_lshlrev_b64 v[4:5], 10, v[140:141]
	s_ashr_i32 s37, s36, 31
	v_lshl_add_u64 v[4:5], v[4:5], 0, s[24:25]
	v_mul_lo_u32 v16, v5, s36
	v_mul_lo_u32 v17, v4, s37
	v_mad_u64_u32 v[4:5], s[6:7], v4, s36, 0
	v_add3_u32 v5, v5, v17, v16
	v_or_b32_e32 v4, v136, v4
	v_mul_lo_u32 v7, v68, s3
	v_mul_lo_u32 v8, v22, s3
	v_mul_lo_u32 v9, v23, s3
	v_mul_lo_u32 v10, v24, s3
	v_mul_lo_u32 v11, v25, s3
	v_mul_lo_u32 v12, v26, s3
	v_mul_lo_u32 v13, v27, s3
	v_mul_lo_u32 v14, v28, s3
	v_lshl_or_b32 v15, v173, 9, v166
	v_lshl_add_u64 v[160:161], v[4:5], 0, v[132:133]
	v_lshl_add_u32 v160, s98, 16, v160
	v_mov_b32_e32 v4, 0
	s_mov_b32 s6, 0
	v_add_u32_e32 v132, v6, v7
	v_add_u32_e32 v141, v6, v8
	v_add_u32_e32 v174, v6, v9
	v_add_u32_e32 v175, v6, v10
	v_add_u32_e32 v176, v6, v11
	v_add_u32_e32 v177, v6, v12
	v_add_u32_e32 v178, v6, v13
	v_add_u32_e32 v179, v6, v14
	v_add_u32_e32 v180, v137, v15
	v_mov_b32_e32 v5, v4
	v_mov_b32_e32 v6, v4
	v_mov_b32_e32 v7, v4
	v_mov_b32_e32 v8, v4
	v_mov_b32_e32 v9, v4
	v_mov_b32_e32 v10, v4
	v_mov_b32_e32 v11, v4
	v_mov_b32_e32 v12, v4
	v_mov_b32_e32 v13, v4
	v_mov_b32_e32 v14, v4
	v_mov_b32_e32 v15, v4
	v_mov_b32_e32 v16, v4
	v_mov_b32_e32 v17, v4
	v_mov_b32_e32 v18, v4
	v_mov_b32_e32 v19, v4
	v_mov_b32_e32 v20, v4
	v_mov_b32_e32 v21, v4
	v_mov_b32_e32 v22, v4
	v_mov_b32_e32 v23, v4
	v_mov_b32_e32 v24, v4
	v_mov_b32_e32 v25, v4
	v_mov_b32_e32 v26, v4
	v_mov_b32_e32 v27, v4
	v_mov_b32_e32 v28, v4
	v_mov_b32_e32 v29, v4
	v_mov_b32_e32 v30, v4
	v_mov_b32_e32 v31, v4
	v_mov_b32_e32 v32, v4
	v_mov_b32_e32 v33, v4
	v_mov_b32_e32 v34, v4
	v_mov_b32_e32 v35, v4
	s_branch .LBB0_890

.LBB0_892:
	v_lshlrev_b32_e32 v36, 14, v173
	v_lshlrev_b32_e32 v37, 12, v140
	v_add3_u32 v36, v167, v36, v37
	s_barrier
	s_nop 4
	ds_write2st64_b32 v36, v4, v5 offset1:1
	ds_write2st64_b32 v36, v6, v7 offset0:2 offset1:3
	ds_write2st64_b32 v36, v8, v9 offset0:4 offset1:5
	ds_write2st64_b32 v36, v10, v11 offset0:6 offset1:7
	ds_write2st64_b32 v36, v12, v13 offset0:8 offset1:9
	ds_write2st64_b32 v36, v14, v15 offset0:10 offset1:11
	ds_write2st64_b32 v36, v16, v17 offset0:12 offset1:13
	ds_write2st64_b32 v36, v18, v19 offset0:14 offset1:15
	ds_write2st64_b32 v36, v20, v21 offset0:16 offset1:17
	ds_write2st64_b32 v36, v22, v23 offset0:18 offset1:19
	ds_write2st64_b32 v36, v24, v25 offset0:20 offset1:21
	ds_write2st64_b32 v36, v26, v27 offset0:22 offset1:23
	ds_write2st64_b32 v36, v28, v29 offset0:24 offset1:25
	ds_write2st64_b32 v36, v30, v31 offset0:26 offset1:27
	ds_write2st64_b32 v36, v32, v33 offset0:28 offset1:29
	ds_write2st64_b32 v36, v34, v35 offset0:30 offset1:31
	v_lshrrev_b32_e32 v5, 3, v138
	v_lshlrev_b32_e32 v4, 3, v172
	v_and_b32_e32 v5, 0xfffff0, v5
	v_and_or_b32 v4, v4, 8, v5
	v_lshl_add_u32 v34, v4, 8, v167
	s_waitcnt lgkmcnt(0)
	s_barrier
	ds_read2st64_b32 v[4:5], v34 offset1:1
	ds_read2st64_b32 v[6:7], v34 offset0:2 offset1:3
	ds_read2st64_b32 v[8:9], v34 offset0:4 offset1:5
	ds_read2st64_b32 v[10:11], v34 offset0:6 offset1:7
	ds_read2st64_b32 v[12:13], v34 offset0:64 offset1:65
	ds_read2st64_b32 v[14:15], v34 offset0:66 offset1:67
	ds_read2st64_b32 v[16:17], v34 offset0:68 offset1:69
	ds_read2st64_b32 v[18:19], v34 offset0:70 offset1:71
	ds_read2st64_b32 v[20:21], v34 offset0:128 offset1:129
	ds_read2st64_b32 v[22:23], v34 offset0:130 offset1:131
	ds_read2st64_b32 v[24:25], v34 offset0:132 offset1:133
	ds_read2st64_b32 v[26:27], v34 offset0:134 offset1:135
	ds_read2st64_b32 v[28:29], v34 offset0:192 offset1:193
	ds_read2st64_b32 v[30:31], v34 offset0:194 offset1:195
	ds_read2st64_b32 v[32:33], v34 offset0:196 offset1:197
	ds_read2st64_b32 v[34:35], v34 offset0:198 offset1:199
	s_waitcnt lgkmcnt(0)
	s_barrier
	s_getreg_b32 s6, hwreg(HW_REG_HW_ID, 0, 6)
	s_and_b32 s6, s6, 63
	s_add_i32 s7, 0, 0x23e00
	s_lshl_b32 s6, s6, 2
	s_add_i32 s6, s7, s6
	v_mov_b32_e32 v36, s6
	v_mov_b32_e32 v37, s13
	flat_load_dword v38, v[36:37] sc0 sc1
	s_waitcnt vmcnt(0)
	s_getreg_b32 s6, hwreg(HW_REG_HW_ID, 0, 6)
	s_and_b32 s6, s6, 63
	s_lshl_b32 s6, s6, 2
	s_add_i32 s7, s7, s6
	v_mov_b32_e32 v36, s7
	flat_load_dword v36, v[36:37] sc0 sc1
	s_waitcnt vmcnt(0)
	v_pk_add_f32 v[4:5], v[4:5], 0 op_sel_hi:[1,0]
	v_pk_add_f32 v[6:7], v[6:7], 0 op_sel_hi:[1,0]
	v_pk_add_f32 v[8:9], v[8:9], 0 op_sel_hi:[1,0]
	v_pk_add_f32 v[10:11], v[10:11], 0 op_sel_hi:[1,0]
	v_pk_add_f32 v[4:5], v[4:5], v[12:13]
	v_pk_add_f32 v[6:7], v[6:7], v[14:15]
	v_pk_add_f32 v[8:9], v[8:9], v[16:17]
	v_pk_add_f32 v[10:11], v[10:11], v[18:19]
	v_pk_add_f32 v[4:5], v[4:5], v[20:21]
	v_pk_add_f32 v[6:7], v[6:7], v[22:23]
	v_pk_add_f32 v[12:13], v[8:9], v[24:25]
	v_pk_add_f32 v[14:15], v[10:11], v[26:27]
	v_pk_add_f32 v[8:9], v[4:5], v[28:29]
	v_pk_add_f32 v[10:11], v[6:7], v[30:31]
	v_pk_add_f32 v[4:5], v[12:13], v[32:33]
	v_pk_add_f32 v[6:7], v[14:15], v[34:35]
	s_cmp_eq_u32 s98, 0
	s_cbranch_scc1 .Lskda_owner
	s_mul_i32 s100, s30, 0xc000
	s_lshl_b32 s101, s98, 14
	s_add_i32 s100, s100, s101
	s_add_i32 s100, s100, 0x613c000
	v_lshl_add_u32 v12, v138, 4, s100
	v_add_u32_e32 v13, 0x2000, v12
	global_store_dwordx4 v12, v[8:11], s[82:83] sc1
	global_store_dwordx4 v13, v[4:7], s[82:83] sc1
	s_waitcnt vmcnt(0)
	s_barrier
	v_cmp_eq_u32_e32 vcc, 0, v138
	s_and_saveexec_b64 vcc, vcc
	s_cbranch_execz .Lskda_harr
	s_lshl_b32 s100, s30, 8
	s_add_i32 s100, s100, 0xc0000
	v_mov_b32_e32 v12, s100
	v_mov_b32_e32 v13, 1
	global_atomic_add v12, v13, s[82:83]
.Lskda_harr:
	s_or_b64 exec, exec, vcc
	s_branch .LBB0_886
.Lskda_owner:
	v_cmp_gt_u32_e32 vcc, 64, v138
	s_and_saveexec_b64 vcc, vcc
	s_cbranch_execz .Lskda_spun
	s_lshl_b32 s100, s30, 8
	s_add_i32 s100, s100, 0xc0000
	v_mov_b32_e32 v12, s100
	s_mov_b32 s101, 0x1000
.Lskda_spin:
	global_load_dword v13, v12, s[82:83] sc1
	s_waitcnt vmcnt(0)
	v_readfirstlane_b32 s100, v13
	s_cmp_ge_u32 s100, 3
	s_cbranch_scc1 .Lskda_spun
	s_sleep 1
	s_add_i32 s101, s101, -1
	s_cmp_gt_i32 s101, 0
	s_cbranch_scc1 .Lskda_spin
.Lskda_spun:
	s_or_b64 exec, exec, vcc
	s_barrier
	s_mul_i32 s100, s30, 0xc000
	s_add_i32 s100, s100, 0x6140000
	v_lshl_add_u32 v12, v138, 4, s100
	v_add_u32_e32 v13, 0x2000, v12
	v_add_u32_e32 v14, 0x4000, v12
	v_add_u32_e32 v15, 0x6000, v12
	v_add_u32_e32 v16, 0x8000, v12
	v_add_u32_e32 v17, 0xa000, v12
	global_load_dwordx4 v[192:195], v12, s[82:83] sc1
	global_load_dwordx4 v[196:199], v13, s[82:83] sc1
	global_load_dwordx4 v[200:203], v14, s[82:83] sc1
	global_load_dwordx4 v[204:207], v15, s[82:83] sc1
	global_load_dwordx4 v[208:211], v16, s[82:83] sc1
	global_load_dwordx4 v[226:229], v17, s[82:83] sc1
	s_waitcnt vmcnt(0)
	v_pk_add_f32 v[8:9], v[8:9], v[192:193]
	v_pk_add_f32 v[10:11], v[10:11], v[194:195]
	v_pk_add_f32 v[4:5], v[4:5], v[196:197]
	v_pk_add_f32 v[6:7], v[6:7], v[198:199]
	v_pk_add_f32 v[8:9], v[8:9], v[200:201]
	v_pk_add_f32 v[10:11], v[10:11], v[202:203]
	v_pk_add_f32 v[4:5], v[4:5], v[204:205]
	v_pk_add_f32 v[6:7], v[6:7], v[206:207]
	v_pk_add_f32 v[8:9], v[8:9], v[208:209]
	v_pk_add_f32 v[10:11], v[10:11], v[210:211]
	v_pk_add_f32 v[4:5], v[4:5], v[226:227]
	v_pk_add_f32 v[6:7], v[6:7], v[228:229]
	v_pk_mul_f32 v[12:13], v[8:9], v[8:9]
	v_pk_mul_f32 v[14:15], v[10:11], v[10:11]
	v_pk_mul_f32 v[16:17], v[4:5], v[4:5]
	v_pk_mul_f32 v[18:19], v[6:7], v[6:7]
	v_add_f32_e32 v16, v16, v17
	v_add_f32_e32 v18, v18, v19
	v_add_f32_e32 v14, v14, v15
	v_add_f32_e32 v12, v12, v13
	v_add_f32_e32 v13, v16, v18
	v_add_f32_e32 v12, v12, v14
	v_add_f32_e32 v13, v12, v13
	ds_bpermute_b32 v15, v169, v13
	v_lshlrev_b32_e32 v14, 2, v212
	s_waitcnt lgkmcnt(0)
	v_readfirstlane_b32 s46, v38
	v_readfirstlane_b32 s6, v36
	s_nop 1
	v_lshl_add_u32 v12, s6, 6, v217
	s_and_saveexec_b64 s[6:7], s[0:1]
	s_cbranch_execz .LBB0_894
	v_add_f32_e32 v13, v13, v15
	v_lshlrev_b32_e32 v15, 3, v12
	v_and_b32_e32 v15, 0x200, v15
	v_add_u32_e32 v15, 0, v15
	v_and_b32_e32 v16, 0xffffff80, v12
	v_add3_u32 v15, v15, v16, v14
	ds_write_b32 v15, v13

.LBB0_1814:
	v_readlane_b32 s4, v244, 3
	s_cmp_gt_i32 s4, 10
	s_cselect_b64 s[6:7], -1, 0
	s_xor_b64 s[0:1], s[0:1], -1
	v_readlane_b32 s5, v244, 4
	s_or_b64 s[0:1], s[6:7], s[0:1]
	s_mov_b64 s[4:5], -1
	s_and_b64 vcc, exec, s[0:1]
	s_cbranch_vccnz .LBB0_1899
	s_add_u32 s8, s82, 0x2600000
	s_addc_u32 s9, s83, 0
	s_cmpk_lt_i32 s2, 0x80
	s_cbranch_scc1 .LBB0_1817
	v_lshrrev_b32_e32 v150, 1, v217
	s_mov_b64 s[4:5], 0
.LBB0_1817:
	s_andn2_b64 vcc, exec, s[4:5]
	s_cbranch_vccnz .LBB0_1843
	s_add_u32 s12, s80, 0x4000000
	s_addc_u32 s13, s81, 0
	s_add_u32 s14, s82, 0x20c000
	v_lshrrev_b32_e32 v2, 3, v217
	s_addc_u32 s15, s83, 0
	v_and_b32_e32 v164, 4, v2
	v_add_u32_e32 v2, 64, v224
	s_add_u32 s16, s82, 0x14000
	v_cmp_lt_i32_e32 vcc, v223, v2
	s_addc_u32 s17, s83, 0
	s_mov_b64 s[10:11], src_shared_base
	v_cndmask_b32_e32 v2, v217, v223, vcc
	s_movk_i32 s3, 0x810
	v_lshlrev_b32_e32 v165, 2, v2
	v_and_b32_e32 v2, 32, v217
	s_add_u32 s18, s56, 0x1000
	s_waitcnt vmcnt(0)
	v_mad_u32_u24 v131, v212, s3, 0
	v_and_b32_e32 v162, 16, v222
	v_lshl_add_u32 v163, v213, 2, 0
	v_cmp_eq_u32_e64 s[0:1], 0, v2
	v_cmp_eq_u32_e64 s[4:5], 0, v213
	s_addc_u32 s19, s57, 0
	s_lshr_b32 s98, s2, 5
	s_and_b32 s99, s2, 31
	s_lshl_b32 s10, s99, 5
	s_lshl_b32 s33, s88, 5
	v_lshlrev_b32_e32 v130, 4, v213
	v_mov_b32_e32 v133, 0
	v_mov_b32_e32 v135, s11
	s_mov_b64 s[20:21], 0x2600800
	s_mov_b64 s[22:23], 0x400
	s_mov_b32 s36, 0xe400000
	s_mov_b32 s37, 0xe401000
	s_mov_b32 s38, 0xe402000
	s_mov_b32 s39, 0xe403000
	s_mov_b64 s[24:25], 0x800
	s_mov_b64 s[26:27], 0x10000
	s_movk_i32 s40, 0x80
	s_movk_i32 s41, 0xffe0
	v_mov_b32_e32 v166, 0x358637bd
	s_mov_b32 s42, 0xf800000
	v_mov_b32_e32 v167, 0x260
	s_and_b32 s28, s2, 31
	s_branch .LBB0_1820

.LBB0_1820:
	s_lshl_b32 s100, s98, 11
	s_add_u32 s100, s8, s100
	s_addc_u32 s101, s9, 0
	s_getreg_b32 s6, hwreg(HW_REG_HW_ID, 0, 6)
	s_and_b32 s6, s6, 63
	s_lshl_b32 s6, s6, 2
	s_add_i32 s6, s6, 0
	s_add_i32 s6, s6, 0x23e00
	v_mov_b32_e32 v134, s6
	flat_load_dword v2, v[134:135] sc0 sc1
	s_waitcnt vmcnt(0)
	s_movk_i32 s6, 0x1000
	s_lshl_b32 s43, s28, 5
	s_mov_b32 s29, 1
	v_mov_b32_e32 v33, 0
	v_mov_b32_e32 v32, 0
	v_mov_b32_e32 v31, 0
	v_mov_b32_e32 v30, 0
	v_mov_b32_e32 v29, 0
	v_mov_b32_e32 v28, 0
	v_mov_b32_e32 v27, 0
	v_mov_b32_e32 v26, 0
	v_mov_b32_e32 v25, 0
	v_mov_b32_e32 v24, 0
	v_mov_b32_e32 v23, 0
	v_mov_b32_e32 v22, 0
	v_mov_b32_e32 v21, 0
	v_mov_b32_e32 v20, 0
	v_mov_b32_e32 v19, 0
	v_mov_b32_e32 v18, 0
	v_mov_b32_e32 v17, 0
	v_mov_b32_e32 v16, 0
	v_mov_b32_e32 v15, 0
	v_mov_b32_e32 v14, 0
	v_mov_b32_e32 v13, 0
	v_mov_b32_e32 v12, 0
	v_mov_b32_e32 v11, 0
	v_mov_b32_e32 v10, 0
	v_mov_b32_e32 v9, 0
	v_mov_b32_e32 v8, 0
	v_mov_b32_e32 v7, 0
	v_mov_b32_e32 v6, 0
	v_mov_b32_e32 v5, 0
	v_mov_b32_e32 v4, 0
	s_waitcnt lgkmcnt(0)
	v_mov_b32_e32 v3, 0
	s_cmp_lt_i32 s29, 1
	v_readfirstlane_b32 s7, v2
	s_nop 1
	v_lshl_add_u32 v134, s7, 6, v217
	v_ashrrev_i32_e32 v66, 7, v134
	v_ashrrev_i32_e32 v168, 6, v134
	v_and_b32_e32 v136, -2, v66
	v_and_b32_e32 v169, 3, v168
	v_ashrrev_i32_e32 v137, 31, v136
	v_mov_b32_e32 v2, 0
	s_cbranch_scc1 .LBB0_1825
	v_add_u32_e32 v6, 0x200, v134
	v_add_u32_e32 v10, 0x600, v134
	v_add_u32_e32 v14, 0xa00, v134
	v_add_u32_e32 v18, 0xe00, v134
	v_lshlrev_b32_e32 v2, 4, v134
	v_ashrrev_i32_e32 v20, 7, v6
	v_add_u32_e32 v8, 0x400, v134
	v_ashrrev_i32_e32 v22, 7, v10
	v_add_u32_e32 v12, 0x800, v134
	v_ashrrev_i32_e32 v24, 7, v14
	v_add_u32_e32 v16, 0xc00, v134
	v_ashrrev_i32_e32 v26, 7, v18
	v_and_b32_e32 v132, 0x7f0, v2
	v_add_u32_e32 v6, s43, v20
	v_ashrrev_i32_e32 v21, 7, v8
	v_add_u32_e32 v10, s43, v22
	v_ashrrev_i32_e32 v23, 7, v12
	v_add_u32_e32 v14, s43, v24
	v_ashrrev_i32_e32 v25, 7, v16
	v_add_u32_e32 v18, s43, v26
	v_lshl_add_u64 v[2:3], s[100:101], 0, v[132:133]
	v_add_u32_e32 v4, s43, v66
	v_mad_i64_i32 v[6:7], s[30:31], v6, s6, 0
	v_add_u32_e32 v8, s43, v21
	v_mad_i64_i32 v[10:11], s[30:31], v10, s6, 0
	v_add_u32_e32 v12, s43, v23
	v_mad_i64_i32 v[14:15], s[30:31], v14, s6, 0
	v_add_u32_e32 v16, s43, v25
	v_mad_i64_i32 v[18:19], s[30:31], v18, s6, 0
	v_mad_i64_i32 v[4:5], s[30:31], v4, s6, 0
	v_mad_i64_i32 v[8:9], s[30:31], v8, s6, 0
	v_mad_i64_i32 v[12:13], s[30:31], v12, s6, 0
	v_mad_i64_i32 v[16:17], s[30:31], v16, s6, 0
	v_lshl_add_u64 v[18:19], v[18:19], 1, v[2:3]
	v_lshl_add_u64 v[14:15], v[14:15], 1, v[2:3]
	v_lshl_add_u64 v[10:11], v[10:11], 1, v[2:3]
	v_lshl_add_u64 v[6:7], v[6:7], 1, v[2:3]
	v_lshl_add_u64 v[16:17], v[16:17], 1, v[2:3]
	global_load_dwordx4 v[62:65], v[18:19], off
	global_load_dwordx4 v[58:61], v[16:17], off
	v_lshl_add_u64 v[12:13], v[12:13], 1, v[2:3]
	global_load_dwordx4 v[54:57], v[14:15], off
	global_load_dwordx4 v[50:53], v[12:13], off
	v_lshl_add_u64 v[8:9], v[8:9], 1, v[2:3]
	global_load_dwordx4 v[46:49], v[10:11], off
	global_load_dwordx4 v[42:45], v[8:9], off
	v_lshl_add_u64 v[2:3], v[4:5], 1, v[2:3]
	global_load_dwordx4 v[38:41], v[6:7], off
	global_load_dwordx4 v[34:37], v[2:3], off
	s_ashr_i32 s7, s6, 31
	v_add_u32_e32 v14, s10, v66
	v_and_b32_e32 v2, 0x7f, v134
	s_ashr_i32 s34, s6, 4
	v_add_u32_e32 v4, 0, v132
	s_lshl_b32 s44, s6, 1
	v_ashrrev_i32_e32 v15, 31, v14
	v_lshlrev_b32_e32 v132, 4, v2
	s_lshr_b64 s[6:7], s[6:7], 31
	v_mad_u64_u32 v[2:3], s[30:31], s44, v14, v[132:133]
	v_mul_lo_u32 v15, s44, v15
	v_mul_lo_u32 v14, s6, v14
	v_add3_u32 v3, v14, v3, v15
	v_add_u32_e32 v14, s10, v20
	v_ashrrev_i32_e32 v15, 31, v14
	v_lshl_add_u64 v[138:139], v[2:3], 0, s[20:21]
	v_mad_u64_u32 v[2:3], s[30:31], s44, v14, v[132:133]
	v_mul_lo_u32 v14, s6, v14
	v_mul_lo_u32 v15, s44, v15
	v_add3_u32 v3, v14, v3, v15
	v_add_u32_e32 v14, s10, v21
	v_ashrrev_i32_e32 v15, 31, v14
	v_lshl_add_u64 v[140:141], v[2:3], 0, s[20:21]
	v_mad_u64_u32 v[2:3], s[30:31], s44, v14, v[132:133]
	v_mul_lo_u32 v14, s6, v14
	v_mul_lo_u32 v15, s44, v15
	v_add3_u32 v3, v14, v3, v15
	v_add_u32_e32 v14, s10, v22
	v_ashrrev_i32_e32 v15, 31, v14
	v_lshl_add_u64 v[142:143], v[2:3], 0, s[20:21]
	v_mad_u64_u32 v[2:3], s[30:31], s44, v14, v[132:133]
	v_mul_lo_u32 v14, s6, v14
	v_mul_lo_u32 v15, s44, v15
	v_add3_u32 v3, v14, v3, v15
	v_add_u32_e32 v14, s10, v23
	v_ashrrev_i32_e32 v15, 31, v14
	v_lshl_add_u64 v[144:145], v[2:3], 0, s[20:21]
	v_mad_u64_u32 v[2:3], s[30:31], s44, v14, v[132:133]
	v_mul_lo_u32 v14, s6, v14
	v_mul_lo_u32 v15, s44, v15
	v_add3_u32 v3, v14, v3, v15
	v_add_u32_e32 v14, s10, v24
	v_ashrrev_i32_e32 v15, 31, v14
	v_lshl_add_u64 v[146:147], v[2:3], 0, s[20:21]
	v_mad_u64_u32 v[2:3], s[30:31], s44, v14, v[132:133]
	v_mul_lo_u32 v14, s6, v14
	v_mul_lo_u32 v15, s44, v15
	v_add3_u32 v3, v14, v3, v15
	v_add_u32_e32 v14, s10, v25
	v_ashrrev_i32_e32 v15, 31, v14
	v_lshl_add_u64 v[148:149], v[2:3], 0, s[20:21]
	v_mad_u64_u32 v[2:3], s[30:31], s44, v14, v[132:133]
	v_mul_lo_u32 v14, s6, v14
	v_mul_lo_u32 v15, s44, v15
	v_add3_u32 v3, v14, v3, v15
	v_add_u32_e32 v14, s10, v26
	v_ashrrev_i32_e32 v15, 31, v14
	v_lshl_add_u64 v[150:151], v[2:3], 0, s[20:21]
	v_mad_u64_u32 v[2:3], s[30:31], s44, v14, v[132:133]
	v_mul_lo_u32 v14, s6, v14
	v_mul_lo_u32 v15, s44, v15
	v_add3_u32 v3, v14, v3, v15
	v_lshl_add_u64 v[152:153], v[2:3], 0, s[20:21]
	v_mad_i64_i32 v[2:3], s[6:7], s34, v136, 0
	v_lshlrev_b64 v[2:3], 10, v[2:3]
	v_lshlrev_b32_e32 v14, 8, v134
	v_or_b32_e32 v2, v130, v2
	v_and_b32_e32 v132, 0xc000, v14
	v_lshl_add_u64 v[154:155], v[2:3], 0, v[132:133]
	v_lshl_add_u32 v154, s98, 16, v154
	v_lshlrev_b64 v[2:3], 10, v[136:137]
	s_ashr_i32 s35, s34, 31
	v_lshl_add_u64 v[2:3], v[2:3], 0, s[22:23]
	v_mul_lo_u32 v14, v3, s34
	v_mul_lo_u32 v15, v2, s35
	v_mad_u64_u32 v[2:3], s[6:7], v2, s34, 0
	v_add3_u32 v3, v3, v15, v14
	v_or_b32_e32 v2, v130, v2
	v_mul_lo_u32 v5, v66, s3
	v_mul_lo_u32 v6, v20, s3
	v_mul_lo_u32 v7, v21, s3
	v_mul_lo_u32 v8, v22, s3
	v_mul_lo_u32 v9, v23, s3
	v_mul_lo_u32 v10, v24, s3
	v_mul_lo_u32 v11, v25, s3
	v_mul_lo_u32 v12, v26, s3
	v_lshl_or_b32 v13, v169, 9, v162
	v_lshl_add_u64 v[156:157], v[2:3], 0, v[132:133]
	v_lshl_add_u32 v156, s98, 16, v156
	v_mov_b32_e32 v2, 0
	s_mov_b32 s6, 0
	v_add_u32_e32 v132, v4, v5
	v_add_u32_e32 v137, v4, v6
	v_add_u32_e32 v170, v4, v7
	v_add_u32_e32 v171, v4, v8
	v_add_u32_e32 v172, v4, v9
	v_add_u32_e32 v173, v4, v10
	v_add_u32_e32 v174, v4, v11
	v_add_u32_e32 v175, v4, v12
	v_add_u32_e32 v176, v131, v13
	v_mov_b32_e32 v3, v2
	v_mov_b32_e32 v4, v2
	v_mov_b32_e32 v5, v2
	v_mov_b32_e32 v6, v2
	v_mov_b32_e32 v7, v2
	v_mov_b32_e32 v8, v2
	v_mov_b32_e32 v9, v2
	v_mov_b32_e32 v10, v2
	v_mov_b32_e32 v11, v2
	v_mov_b32_e32 v12, v2
	v_mov_b32_e32 v13, v2
	v_mov_b32_e32 v14, v2
	v_mov_b32_e32 v15, v2
	v_mov_b32_e32 v16, v2
	v_mov_b32_e32 v17, v2
	v_mov_b32_e32 v18, v2
	v_mov_b32_e32 v19, v2
	v_mov_b32_e32 v20, v2
	v_mov_b32_e32 v21, v2
	v_mov_b32_e32 v22, v2
	v_mov_b32_e32 v23, v2
	v_mov_b32_e32 v24, v2
	v_mov_b32_e32 v25, v2
	v_mov_b32_e32 v26, v2
	v_mov_b32_e32 v27, v2
	v_mov_b32_e32 v28, v2
	v_mov_b32_e32 v29, v2
	v_mov_b32_e32 v30, v2
	v_mov_b32_e32 v31, v2
	v_mov_b32_e32 v32, v2
	v_mov_b32_e32 v33, v2
	s_branch .LBB0_1823

.LBB0_1825:
	v_lshlrev_b32_e32 v34, 14, v169
	v_lshlrev_b32_e32 v35, 12, v136
	v_add3_u32 v34, v163, v34, v35
	s_barrier
	s_nop 4
	ds_write2st64_b32 v34, v2, v3 offset1:1
	ds_write2st64_b32 v34, v4, v5 offset0:2 offset1:3
	ds_write2st64_b32 v34, v6, v7 offset0:4 offset1:5
	ds_write2st64_b32 v34, v8, v9 offset0:6 offset1:7
	ds_write2st64_b32 v34, v10, v11 offset0:8 offset1:9
	ds_write2st64_b32 v34, v12, v13 offset0:10 offset1:11
	ds_write2st64_b32 v34, v14, v15 offset0:12 offset1:13
	ds_write2st64_b32 v34, v16, v17 offset0:14 offset1:15
	ds_write2st64_b32 v34, v18, v19 offset0:16 offset1:17
	ds_write2st64_b32 v34, v20, v21 offset0:18 offset1:19
	ds_write2st64_b32 v34, v22, v23 offset0:20 offset1:21
	ds_write2st64_b32 v34, v24, v25 offset0:22 offset1:23
	ds_write2st64_b32 v34, v26, v27 offset0:24 offset1:25
	ds_write2st64_b32 v34, v28, v29 offset0:26 offset1:27
	ds_write2st64_b32 v34, v30, v31 offset0:28 offset1:29
	ds_write2st64_b32 v34, v32, v33 offset0:30 offset1:31
	v_lshrrev_b32_e32 v3, 3, v134
	v_lshlrev_b32_e32 v2, 3, v168
	v_and_b32_e32 v3, 0xfffff0, v3
	v_and_or_b32 v2, v2, 8, v3
	v_lshl_add_u32 v32, v2, 8, v163
	s_waitcnt lgkmcnt(0)
	s_barrier
	ds_read2st64_b32 v[2:3], v32 offset1:1
	ds_read2st64_b32 v[4:5], v32 offset0:2 offset1:3
	ds_read2st64_b32 v[10:11], v32 offset0:4 offset1:5
	ds_read2st64_b32 v[12:13], v32 offset0:6 offset1:7
	ds_read2st64_b32 v[6:7], v32 offset0:64 offset1:65
	ds_read2st64_b32 v[8:9], v32 offset0:66 offset1:67
	ds_read2st64_b32 v[14:15], v32 offset0:68 offset1:69
	ds_read2st64_b32 v[16:17], v32 offset0:70 offset1:71
	ds_read2st64_b32 v[18:19], v32 offset0:128 offset1:129
	ds_read2st64_b32 v[20:21], v32 offset0:130 offset1:131
	ds_read2st64_b32 v[22:23], v32 offset0:132 offset1:133
	ds_read2st64_b32 v[24:25], v32 offset0:134 offset1:135
	ds_read2st64_b32 v[26:27], v32 offset0:192 offset1:193
	ds_read2st64_b32 v[28:29], v32 offset0:194 offset1:195
	ds_read2st64_b32 v[30:31], v32 offset0:196 offset1:197
	ds_read2st64_b32 v[32:33], v32 offset0:198 offset1:199
	s_waitcnt lgkmcnt(0)
	s_barrier
	s_getreg_b32 s6, hwreg(HW_REG_HW_ID, 0, 6)
	s_and_b32 s6, s6, 63
	s_add_i32 s7, 0, 0x23e00
	s_lshl_b32 s6, s6, 2
	s_add_i32 s6, s7, s6
	v_mov_b32_e32 v34, s6
	v_mov_b32_e32 v35, s11
	flat_load_dword v36, v[34:35] sc0 sc1
	s_waitcnt vmcnt(0)
	s_getreg_b32 s6, hwreg(HW_REG_HW_ID, 0, 6)
	s_and_b32 s6, s6, 63
	s_lshl_b32 s6, s6, 2
	s_add_i32 s7, s7, s6
	v_mov_b32_e32 v34, s7
	flat_load_dword v34, v[34:35] sc0 sc1
	s_waitcnt vmcnt(0)
	v_pk_add_f32 v[2:3], v[2:3], 0 op_sel_hi:[1,0]
	s_waitcnt lgkmcnt(0)
	v_readfirstlane_b32 s44, v36
	v_pk_add_f32 v[2:3], v[2:3], v[6:7]
	v_readfirstlane_b32 s6, v34
	v_pk_add_f32 v[2:3], v[2:3], v[18:19]
	s_nop 0
	v_pk_add_f32 v[6:7], v[2:3], v[26:27]
	v_pk_add_f32 v[2:3], v[4:5], 0 op_sel_hi:[1,0]
	v_pk_add_f32 v[4:5], v[12:13], 0 op_sel_hi:[1,0]
	v_pk_add_f32 v[2:3], v[2:3], v[8:9]
	v_pk_add_f32 v[4:5], v[4:5], v[16:17]
	v_pk_add_f32 v[2:3], v[2:3], v[20:21]
	v_pk_add_f32 v[4:5], v[4:5], v[24:25]
	v_pk_add_f32 v[8:9], v[2:3], v[28:29]
	v_pk_add_f32 v[2:3], v[10:11], 0 op_sel_hi:[1,0]
	v_pk_add_f32 v[4:5], v[4:5], v[32:33]
	v_pk_add_f32 v[2:3], v[2:3], v[14:15]
	v_pk_add_f32 v[2:3], v[2:3], v[22:23]
	v_pk_add_f32 v[2:3], v[2:3], v[30:31]
	s_cmp_eq_u32 s98, 0
	s_cbranch_scc1 .Lskdb_owner
	s_mul_i32 s100, s28, 0xc000
	s_lshl_b32 s101, s98, 14
	s_add_i32 s100, s100, s101
	s_add_i32 s100, s100, 0x613c000
	v_lshl_add_u32 v12, v134, 4, s100
	v_add_u32_e32 v13, 0x2000, v12
	global_store_dwordx4 v12, v[6:9], s[82:83] sc1
	global_store_dwordx4 v13, v[2:5], s[82:83] sc1
	s_waitcnt vmcnt(0)
	s_barrier
	v_cmp_eq_u32_e32 vcc, 0, v134
	s_and_saveexec_b64 vcc, vcc
	s_cbranch_execz .Lskdb_harr
	s_lshl_b32 s100, s28, 8
	s_add_i32 s100, s100, 0xc4000
	v_mov_b32_e32 v12, s100
	v_mov_b32_e32 v13, 1
	global_atomic_add v12, v13, s[82:83]

.Lskdb_owner:
	v_cmp_gt_u32_e32 vcc, 64, v134
	s_and_saveexec_b64 vcc, vcc
	s_cbranch_execz .Lskdb_spun
	s_lshl_b32 s100, s28, 8
	s_add_i32 s100, s100, 0xc4000
	v_mov_b32_e32 v12, s100
	s_mov_b32 s101, 0x1000

.Lskdb_spun:
	s_or_b64 exec, exec, vcc
	s_barrier
	s_mul_i32 s100, s28, 0xc000
	s_add_i32 s100, s100, 0x6140000
	v_lshl_add_u32 v12, v134, 4, s100
	v_add_u32_e32 v13, 0x2000, v12
	v_add_u32_e32 v14, 0x4000, v12
	v_add_u32_e32 v15, 0x6000, v12
	v_add_u32_e32 v16, 0x8000, v12
	v_add_u32_e32 v17, 0xa000, v12
	global_load_dwordx4 v[192:195], v12, s[82:83] sc1
	global_load_dwordx4 v[196:199], v13, s[82:83] sc1
	global_load_dwordx4 v[200:203], v14, s[82:83] sc1
	global_load_dwordx4 v[204:207], v15, s[82:83] sc1
	global_load_dwordx4 v[208:211], v16, s[82:83] sc1
	global_load_dwordx4 v[226:229], v17, s[82:83] sc1
	s_waitcnt vmcnt(0)
	v_pk_add_f32 v[6:7], v[6:7], v[192:193]
	v_pk_add_f32 v[8:9], v[8:9], v[194:195]
	v_pk_add_f32 v[2:3], v[2:3], v[196:197]
	v_pk_add_f32 v[4:5], v[4:5], v[198:199]
	v_pk_add_f32 v[6:7], v[6:7], v[200:201]
	v_pk_add_f32 v[8:9], v[8:9], v[202:203]
	v_pk_add_f32 v[2:3], v[2:3], v[204:205]
	v_pk_add_f32 v[4:5], v[4:5], v[206:207]
	v_pk_add_f32 v[6:7], v[6:7], v[208:209]
	v_pk_add_f32 v[8:9], v[8:9], v[210:211]
	v_pk_add_f32 v[2:3], v[2:3], v[226:227]
	v_pk_add_f32 v[4:5], v[4:5], v[228:229]
	v_pk_mul_f32 v[10:11], v[6:7], v[6:7]
	v_pk_mul_f32 v[12:13], v[8:9], v[8:9]
	v_pk_mul_f32 v[16:17], v[4:5], v[4:5]
	v_pk_mul_f32 v[14:15], v[2:3], v[2:3]
	v_add_f32_e32 v16, v16, v17
	v_add_f32_e32 v14, v14, v15
	v_add_f32_e32 v12, v12, v13
	v_add_f32_e32 v10, v10, v11
	v_add_f32_e32 v14, v14, v16
	v_add_f32_e32 v10, v10, v12
	v_add_f32_e32 v11, v10, v14
	ds_bpermute_b32 v12, v165, v11
	v_lshl_add_u32 v10, s6, 6, v217
	s_and_saveexec_b64 s[6:7], s[0:1]
	s_cbranch_execz .LBB0_1827
	s_waitcnt lgkmcnt(0)
	v_add_f32_e32 v11, v11, v12
	v_lshlrev_b32_e32 v12, 3, v10
	v_and_b32_e32 v12, 0x200, v12
	v_add_u32_e32 v12, 0, v12
	v_and_b32_e32 v13, 0xffffff80, v10
	v_lshlrev_b32_e32 v14, 2, v212
	v_add3_u32 v12, v12, v13, v14
	ds_write_b32 v12, v11

	.amdhsa_kernel _Z8yoco_fwd6Params
		.amdhsa_group_segment_fixed_size 0
		.amdhsa_private_segment_fixed_size 0
		.amdhsa_kernarg_size 472
		.amdhsa_user_sgpr_count 2
		.amdhsa_user_sgpr_dispatch_ptr 0
		.amdhsa_user_sgpr_queue_ptr 0
		.amdhsa_user_sgpr_kernarg_segment_ptr 1
		.amdhsa_user_sgpr_dispatch_id 0
		.amdhsa_user_sgpr_kernarg_preload_length 0
		.amdhsa_user_sgpr_kernarg_preload_offset 0
		.amdhsa_user_sgpr_private_segment_size 0
		.amdhsa_uses_dynamic_stack 0
		.amdhsa_enable_private_segment 0
		.amdhsa_system_sgpr_workgroup_id_x 1
		.amdhsa_system_sgpr_workgroup_id_y 0
		.amdhsa_system_sgpr_workgroup_id_z 0
		.amdhsa_system_sgpr_workgroup_info 0
		.amdhsa_system_vgpr_workitem_id 2
		.amdhsa_next_free_vgpr 245
		.amdhsa_next_free_sgpr 102
		.amdhsa_accum_offset 248
		.amdhsa_reserve_vcc 1
		.amdhsa_float_round_mode_32 0
		.amdhsa_float_round_mode_16_64 0
		.amdhsa_float_denorm_mode_32 3
		.amdhsa_float_denorm_mode_16_64 3
		.amdhsa_dx10_clamp 1
		.amdhsa_ieee_mode 1
		.amdhsa_fp16_overflow 0
		.amdhsa_tg_split 0
		.amdhsa_exception_fp_ieee_invalid_op 0
		.amdhsa_exception_fp_denorm_src 0
		.amdhsa_exception_fp_ieee_div_zero 0
		.amdhsa_exception_fp_ieee_overflow 0
		.amdhsa_exception_fp_ieee_underflow 0
		.amdhsa_exception_fp_ieee_inexact 0
		.amdhsa_exception_int_div_zero 0
	.end_amdhsa_kernel

amdhsa.kernels:
  - .agpr_count:     0
    .args:
      - .offset:         0
        .size:           216
        .value_kind:     by_value
      - .offset:         216
        .size:           4
        .value_kind:     hidden_block_count_x
      - .offset:         220
        .size:           4
        .value_kind:     hidden_block_count_y
      - .offset:         224
        .size:           4
        .value_kind:     hidden_block_count_z
      - .offset:         228
        .size:           2
        .value_kind:     hidden_group_size_x
      - .offset:         230
        .size:           2
        .value_kind:     hidden_group_size_y
      - .offset:         232
        .size:           2
        .value_kind:     hidden_group_size_z
      - .offset:         234
        .size:           2
        .value_kind:     hidden_remainder_x
      - .offset:         236
        .size:           2
        .value_kind:     hidden_remainder_y
      - .offset:         238
        .size:           2
        .value_kind:     hidden_remainder_z
      - .offset:         256
        .size:           8
        .value_kind:     hidden_global_offset_x
      - .offset:         264
        .size:           8
        .value_kind:     hidden_global_offset_y
      - .offset:         272
        .size:           8
        .value_kind:     hidden_global_offset_z
      - .offset:         280
        .size:           2
        .value_kind:     hidden_grid_dims
      - .offset:         304
        .size:           8
        .value_kind:     hidden_multigrid_sync_arg
      - .offset:         336
        .size:           4
        .value_kind:     hidden_dynamic_lds_size
    .group_segment_fixed_size: 0
    .kernarg_segment_align: 8
    .kernarg_segment_size: 472
    .language:       OpenCL C
    .language_version:
      - 2
      - 0
    .max_flat_workgroup_size: 512
    .name:           _Z8yoco_fwd6Params
    .private_segment_fixed_size: 0
    .sgpr_count:     108
    .sgpr_spill_count: 56
    .symbol:         _Z8yoco_fwd6Params.kd
    .uniform_work_group_size: 1
    .uses_dynamic_stack: false
    .vgpr_count:     245
    .vgpr_spill_count: 0
    .wavefront_size: 64
